# weight-conversion item loop in the FFN-down tail: next-item prefetch made real (g/be loads hoisted above the prefetch, LDS-write waits count the prefetch as outstanding, latch waits for the prefetch o
# speedup vs baseline: 1.0065x; 1.0028x over previous
; #define LAS __attribute__((address_space(3)))
; __device__ __forceinline__ void p0_item_process(const PItem& it, int lane, const f32x4 (&v)[8], LAS float* scr) {
;     LAS float* gl = scr + 64 * 36 + 32; LAS float* bl = gl + 64;
;     ...
; #pragma unroll
;     for (int i = 0; i < 8; ++i) *(LAS f32x4*)(scr + SCR_ROW(8 * i + (lane >> 3)) + 4 * (lane & 7)) = v[i];
;     gl[lane] = it.g ? it.g[it.k0 + lane] : 1.f; bl[lane] = it.be ? it.be[it.k0 + lane] : 0.f;
; __device__ __forceinline__ void p0_convert(const Frame& F, const Args& a, int it_lo, int it_hi, int widx, int nw, LAS float* scr) {
;     ...
;         for (int it = it0; it < itend; it += nw) {
;             const bool more = it + nw < itend;
;             PItem nxt = cur; f32x4 vn[8];
;             if (more) { nxt = p0_decode(a, it + nw); p0_item_load(nxt, F.lane, vn); }
;             p0_item_process(cur, F.lane, vc, scr);
.LBB0_1567:
	v_add_u32_e32 v232, s16, v67
	v_ashrrev_i32_e32 v233, 31, v232
	v_mov_b32_e32 v230, 1.0
	v_mov_b32_e32 v231, 0
	s_cmp_eq_u64 s[64:65], 0
	s_cbranch_scc1 .Lcv_ng_fd
	v_lshl_add_u64 v[234:235], v[232:233], 2, s[64:65]
	global_load_dword v230, v[234:235], off
.Lcv_ng_fd:
	s_cmp_eq_u64 s[84:85], 0
	s_cbranch_scc1 .Lcv_nb_fd
	v_lshl_add_u64 v[234:235], v[232:233], 2, s[84:85]
	global_load_dword v231, v[234:235], off

; #define LAS __attribute__((address_space(3)))
; #define LDS_WAIT() asm volatile("s_waitcnt lgkmcnt(0)" ::: "memory")
; __device__ __forceinline__ void p0_item_process(const PItem& it, int lane, const f32x4 (&v)[8], LAS float* scr) {
;     LAS float* gl = scr + 64 * 36 + 32; LAS float* bl = gl + 64;
;     ...
; #pragma unroll
;     for (int i = 0; i < 8; ++i) *(LAS f32x4*)(scr + SCR_ROW(8 * i + (lane >> 3)) + 4 * (lane & 7)) = v[i];
;     gl[lane] = it.g ? it.g[it.k0 + lane] : 1.f; bl[lane] = it.be ? it.be[it.k0 + lane] : 0.f;
;     LDS_WAIT(); asm volatile("" ::: "memory");
.LBB0_1585:
	s_waitcnt vmcnt(15)
	ds_write_b128 v78, v[58:61]
	s_waitcnt vmcnt(14)
	ds_write_b128 v79, v[42:45] offset:16
	s_waitcnt vmcnt(13)
	ds_write_b128 v80, v[54:57] offset:32
	s_waitcnt vmcnt(12)
	ds_write_b128 v81, v[38:41] offset:48
	s_waitcnt vmcnt(11)
	ds_write_b128 v82, v[50:53] offset:64
	s_waitcnt vmcnt(10)
	ds_write_b128 v83, v[34:37] offset:80
	s_waitcnt vmcnt(9)
	ds_write_b128 v84, v[46:49] offset:96
	s_waitcnt vmcnt(8)
	ds_write_b128 v85, v[62:65] offset:112
	s_cmp_lg_u64 s[84:85], 0
	s_cselect_b64 s[64:65], -1, 0
	s_waitcnt vmcnt(8)
	ds_write_b32 v86, v230 offset:9344
	ds_write_b32 v86, v231 offset:9600
	s_waitcnt lgkmcnt(0)
	s_cmp_eq_u64 s[20:21], 0
	s_cbranch_scc1 .LBB0_1598
	v_mov_b32_e32 v34, 0
	s_mov_b32 s0, 0
	v_mov_b32_e32 v36, v90
	v_mov_b32_e32 v35, v34

; #define LAS __attribute__((address_space(3)))
; #define LDS_WAIT() asm volatile("s_waitcnt lgkmcnt(0)" ::: "memory")
; __device__ __forceinline__ unsigned pk2(float lo, float hi) { const f32x2_cv v = {lo, hi}; const bf16x2_cv b = __builtin_convertvector(v, bf16x2_cv); return __builtin_bit_cast(unsigned, b); }
; __device__ __forceinline__ void st16_wt(void* p, f32x4 v) { asm volatile("global_store_dwordx4 %0, %1, off sc1\n\ts_nop 1" :: "v"(p), "v"(v) : "memory"); }
; __device__ __forceinline__ void p0_item_process(const PItem& it, int lane, const f32x4 (&v)[8], LAS float* scr) {
;     ...
;     const int c = lane & 7;
;     const f32x4 g0 = *(const LAS f32x4*)(gl + 8 * c), g1 = *(const LAS f32x4*)(gl + 8 * c + 4);
; #pragma unroll
;     for (int j = 0; j < 4; ++j) { const int n = (lane >> 3) + 8 * j; const LAS float* sp = scr + SCR_ROW(8 * c) + n;
;         v4u o; o.x = pk2(sp[0 * 36] * g0[0], sp[1 * 36] * g0[1]); o.y = pk2(sp[2 * 36] * g0[2], sp[3 * 36] * g0[3]); o.z = pk2(sp[4 * 36] * g1[0], sp[5 * 36] * g1[1]); o.w = pk2(sp[6 * 36] * g1[2], sp[7 * 36] * g1[3]);
;         st16_wt((void*)(it.WT + (size_t)(it.drow0 + n) * it.K + it.k0 + 8 * c), __builtin_bit_cast(f32x4, o)); }
;     LDS_WAIT(); asm volatile("" ::: "memory");
; __device__ __forceinline__ void p0_convert(const Frame& F, const Args& a, int it_lo, int it_hi, int widx, int nw, LAS float* scr) {
;     ...
;             if (more) { cur = nxt;
; #pragma unroll
;                 for (int i = 0; i < 8; ++i) vc[i] = vn[i]; }
.LBB0_1598:
	ds_read2_b32 v[42:43], v88 offset1:36
	s_waitcnt lgkmcnt(1)
	ds_read_b128 v[34:37], v87 offset:9344
	ds_read_b128 v[38:41], v87 offset:9360
	ds_read2_b32 v[44:45], v88 offset0:72 offset1:108
	ds_read2_b32 v[46:47], v88 offset0:144 offset1:180
	ds_read2_b32 v[48:49], v88 offset0:216 offset1:252
	s_waitcnt lgkmcnt(4)
	v_pk_mul_f32 v[42:43], v[34:35], v[42:43]
	s_ashr_i32 s17, s16, 31
	s_waitcnt lgkmcnt(2)
	v_pk_mul_f32 v[44:45], v[36:37], v[44:45]
	v_cvt_pk_bf16_f32 v42, v42, v43
	v_cvt_pk_bf16_f32 v43, v44, v45
	s_waitcnt lgkmcnt(1)
	v_pk_mul_f32 v[44:45], v[38:39], v[46:47]
	s_waitcnt lgkmcnt(0)
	v_pk_mul_f32 v[46:47], v[40:41], v[48:49]
	v_cvt_pk_bf16_f32 v44, v44, v45
	v_cvt_pk_bf16_f32 v45, v46, v47
	v_add_u32_e32 v46, s12, v70
	v_ashrrev_i32_e32 v49, 31, v46
	v_mad_u64_u32 v[46:47], s[0:1], v46, s40, 0
	v_mov_b32_e32 v48, v47
	v_mad_u64_u32 v[48:49], s[0:1], v49, s40, v[48:49]
	v_mov_b32_e32 v47, v48
	v_lshl_add_u64 v[46:47], v[46:47], 1, s[14:15]
	s_lshl_b64 s[16:17], s[16:17], 1
	v_lshl_add_u64 v[46:47], v[46:47], 0, s[16:17]
	v_lshl_add_u64 v[46:47], v[46:47], 0, v[0:1]
	global_store_dwordx4 v[46:47], v[42:45], off sc1
	s_nop 1
	ds_read2_b32 v[42:43], v88 offset0:8 offset1:44
	ds_read2_b32 v[44:45], v88 offset0:80 offset1:116
	v_add_u32_e32 v50, 0x200, v88
	ds_read2_b32 v[46:47], v88 offset0:152 offset1:188
	ds_read2_b32 v[48:49], v50 offset0:96 offset1:132
	s_waitcnt lgkmcnt(3)
	v_pk_mul_f32 v[42:43], v[34:35], v[42:43]
	s_waitcnt lgkmcnt(2)
	v_pk_mul_f32 v[44:45], v[36:37], v[44:45]
	v_cvt_pk_bf16_f32 v42, v42, v43
	v_cvt_pk_bf16_f32 v43, v44, v45
	s_waitcnt lgkmcnt(1)
	v_pk_mul_f32 v[44:45], v[38:39], v[46:47]
	s_waitcnt lgkmcnt(0)
	v_pk_mul_f32 v[46:47], v[40:41], v[48:49]
	v_cvt_pk_bf16_f32 v44, v44, v45
	v_cvt_pk_bf16_f32 v45, v46, v47
	v_add_u32_e32 v46, s12, v71
	v_ashrrev_i32_e32 v49, 31, v46
	v_mad_u64_u32 v[46:47], s[0:1], v46, s40, 0
	v_mov_b32_e32 v48, v47
	v_mad_u64_u32 v[48:49], s[0:1], v49, s40, v[48:49]
	v_mov_b32_e32 v47, v48
	v_lshl_add_u64 v[46:47], v[46:47], 1, s[14:15]
	v_lshl_add_u64 v[46:47], v[46:47], 0, s[16:17]
	v_lshl_add_u64 v[46:47], v[46:47], 0, v[0:1]
	global_store_dwordx4 v[46:47], v[42:45], off sc1
	s_nop 1
	ds_read2_b32 v[42:43], v88 offset0:16 offset1:52
	ds_read2_b32 v[44:45], v88 offset0:88 offset1:124
	ds_read2_b32 v[46:47], v88 offset0:160 offset1:196
	ds_read2_b32 v[48:49], v50 offset0:104 offset1:140
	s_andn2_b64 vcc, exec, s[34:35]
	s_waitcnt lgkmcnt(3)
	v_pk_mul_f32 v[42:43], v[34:35], v[42:43]
	s_waitcnt lgkmcnt(2)
	v_pk_mul_f32 v[44:45], v[36:37], v[44:45]
	v_cvt_pk_bf16_f32 v42, v42, v43
	v_cvt_pk_bf16_f32 v43, v44, v45
	s_waitcnt lgkmcnt(1)
	v_pk_mul_f32 v[44:45], v[38:39], v[46:47]
	s_waitcnt lgkmcnt(0)
	v_pk_mul_f32 v[46:47], v[40:41], v[48:49]
	v_cvt_pk_bf16_f32 v44, v44, v45
	v_cvt_pk_bf16_f32 v45, v46, v47
	v_add_u32_e32 v46, s12, v72
	v_ashrrev_i32_e32 v49, 31, v46
	v_mad_u64_u32 v[46:47], s[0:1], v46, s40, 0
	v_mov_b32_e32 v48, v47
	v_mad_u64_u32 v[48:49], s[0:1], v49, s40, v[48:49]
	v_mov_b32_e32 v47, v48
	v_lshl_add_u64 v[46:47], v[46:47], 1, s[14:15]
	v_lshl_add_u64 v[46:47], v[46:47], 0, s[16:17]
	v_lshl_add_u64 v[46:47], v[46:47], 0, v[0:1]
	global_store_dwordx4 v[46:47], v[42:45], off sc1
	s_nop 1
	ds_read2_b32 v[42:43], v88 offset0:24 offset1:60
	ds_read2_b32 v[44:45], v88 offset0:96 offset1:132
	ds_read2_b32 v[46:47], v50 offset0:112 offset1:148
	s_waitcnt lgkmcnt(2)
	v_pk_mul_f32 v[34:35], v[34:35], v[42:43]
	ds_read2_b32 v[42:43], v88 offset0:168 offset1:204
	s_waitcnt lgkmcnt(2)
	v_pk_mul_f32 v[36:37], v[36:37], v[44:45]
	v_cvt_pk_bf16_f32 v34, v34, v35
	v_cvt_pk_bf16_f32 v35, v36, v37
	s_waitcnt lgkmcnt(0)
	v_pk_mul_f32 v[36:37], v[38:39], v[42:43]
	v_pk_mul_f32 v[38:39], v[40:41], v[46:47]
	v_cvt_pk_bf16_f32 v36, v36, v37
	v_cvt_pk_bf16_f32 v37, v38, v39
	v_add_u32_e32 v38, s12, v73
	v_ashrrev_i32_e32 v41, 31, v38
	v_mad_u64_u32 v[38:39], s[0:1], v38, s40, 0
	v_mov_b32_e32 v40, v39
	v_mad_u64_u32 v[40:41], s[0:1], v41, s40, v[40:41]
	v_mov_b32_e32 v39, v40
	v_lshl_add_u64 v[38:39], v[38:39], 1, s[14:15]
	v_lshl_add_u64 v[38:39], v[38:39], 0, s[16:17]
	v_lshl_add_u64 v[38:39], v[38:39], 0, v[0:1]
	global_store_dwordx4 v[38:39], v[34:37], off sc1
	s_nop 1
	s_waitcnt lgkmcnt(0)
	s_mov_b64 s[12:13], -1
	s_cbranch_vccnz .LBB0_1566
	s_waitcnt vmcnt(4)
	s_mov_b64 s[12:13], 0
	v_mov_b32_e32 v49, v33
	v_mov_b32_e32 v48, v32
	v_mov_b32_e32 v47, v31
	v_mov_b32_e32 v46, v30
	v_mov_b32_e32 v37, v21
	v_mov_b32_e32 v36, v20
	v_mov_b32_e32 v35, v19
	v_mov_b32_e32 v34, v18
	v_mov_b32_e32 v53, v25
	v_mov_b32_e32 v52, v24
	v_mov_b32_e32 v51, v23
	v_mov_b32_e32 v50, v22
	v_mov_b32_e32 v41, v13
	v_mov_b32_e32 v40, v12
	v_mov_b32_e32 v39, v11
	v_mov_b32_e32 v38, v10
	v_mov_b32_e32 v57, v17
	v_mov_b32_e32 v56, v16
	v_mov_b32_e32 v55, v15
	v_mov_b32_e32 v54, v14
	v_mov_b32_e32 v45, v5
	v_mov_b32_e32 v44, v4
	v_mov_b32_e32 v43, v3
	v_mov_b32_e32 v42, v2
	v_mov_b32_e32 v61, v9
	v_mov_b32_e32 v60, v8
	v_mov_b32_e32 v59, v7
	v_mov_b32_e32 v58, v6
	s_branch .LBB0_1566
.Lcv_np_fd:
	s_waitcnt vmcnt(0)
	s_branch .LBB0_1585
